# P3 loop: PV MFMAs key-block-major, packed P written straight into MFMA operand registers (no rotation movs), V address/first fragment reads behind the p0 QK chain
# speedup vs baseline: 1.0145x; 1.0145x over previous
.LBB0_318:
	s_or_b32 s0, s78, 31
	s_or_b32 s1, s2, 64
	s_cmp_gt_u32 s1, s0
	s_cselect_b64 s[70:71], -1, 0
	s_cmp_lg_u64 s[70:71], 0
	s_subb_u32 s82, s33, 0
	s_sub_i32 s0, s72, s2
	v_cvt_f32_i32_e32 v38, s0
	v_lshrrev_b32_e32 v35, 2, v35
	v_lshlrev_b32_e32 v45, 1, v211
	v_and_b32_e32 v44, 12, v33
	v_fma_f32 v40, v208, v38, -v207
	v_fmamk_f32 v41, v208, 0x42000000, v40
	v_add_f32_e32 v16, v40, v16
	v_add_f32_e32 v0, v41, v0
	v_exp_f32_e32 v42, v16
	v_exp_f32_e32 v43, v0
	v_add_f32_e32 v0, v40, v17
	v_add_f32_e32 v1, v41, v1
	v_exp_f32_e32 v0, v0
	v_exp_f32_e32 v16, v1
	v_add_f32_e32 v17, v43, v42
	v_mov_b32_e32 v1, v113
	v_add_f32_e32 v2, v41, v2
	v_pk_add_f32 v[38:39], v[16:17], v[0:1]
	v_add_f32_e32 v1, v40, v18
	v_pk_add_f32 v[38:39], v[38:39], v[38:39] op_sel_hi:[0,1]
	v_exp_f32_e32 v17, v2
	v_add_f32_e32 v2, v40, v19
	v_exp_f32_e32 v1, v1
	v_exp_f32_e32 v38, v2
	v_add_f32_e32 v2, v41, v3
	v_exp_f32_e32 v2, v2
	v_add_f32_e32 v3, v17, v1
	v_add_f32_e32 v4, v41, v4
	v_add_f32_e32 v6, v41, v6
	v_pk_add_f32 v[18:19], v[2:3], v[38:39]
	v_add_f32_e32 v3, v40, v20
	v_pk_add_f32 v[18:19], v[18:19], v[18:19] op_sel_hi:[0,1]
	v_exp_f32_e32 v39, v4
	v_add_f32_e32 v4, v40, v21
	v_exp_f32_e32 v3, v3
	v_exp_f32_e32 v18, v4
	v_add_f32_e32 v4, v41, v5
	v_exp_f32_e32 v4, v4
	v_or_b32_e32 v5, v34, v35
	v_lshlrev_b32_e32 v35, 8, v5
	v_add_f32_e32 v5, v39, v3
	v_pk_add_f32 v[20:21], v[4:5], v[18:19]
	v_add_f32_e32 v5, v40, v22
	v_pk_add_f32 v[20:21], v[20:21], v[20:21] op_sel_hi:[0,1]
	v_exp_f32_e32 v19, v6
	v_add_f32_e32 v6, v40, v23
	v_exp_f32_e32 v5, v5
	v_exp_f32_e32 v20, v6
	v_add_f32_e32 v6, v41, v7
	v_exp_f32_e32 v6, v6
	v_add_f32_e32 v7, v19, v5
	v_add_f32_e32 v8, v41, v8
	v_add_f32_e32 v10, v41, v10
	v_pk_add_f32 v[22:23], v[6:7], v[20:21]
	v_add_f32_e32 v7, v40, v24
	v_pk_add_f32 v[22:23], v[22:23], v[22:23] op_sel_hi:[0,1]
	v_exp_f32_e32 v21, v8
	v_add_f32_e32 v8, v40, v25
	v_exp_f32_e32 v7, v7
	v_exp_f32_e32 v22, v8
	v_add_f32_e32 v8, v41, v9
	v_exp_f32_e32 v8, v8
	v_add_f32_e32 v9, v21, v7
	v_and_b32_e32 v45, 2, v45
	v_and_b32_e32 v37, 1, v37
	v_pk_add_f32 v[24:25], v[8:9], v[22:23]
	v_add_f32_e32 v9, v40, v26
	v_pk_add_f32 v[24:25], v[24:25], v[24:25] op_sel_hi:[0,1]
	v_exp_f32_e32 v23, v10
	v_add_f32_e32 v10, v40, v27
	v_exp_f32_e32 v9, v9
	v_exp_f32_e32 v24, v10
	v_add_f32_e32 v10, v41, v11
	v_exp_f32_e32 v10, v10
	v_or3_b32 v11, v44, v45, v37
	v_lshlrev_b32_e32 v37, 4, v11
	v_add_f32_e32 v11, v23, v9
	v_pk_add_f32 v[26:27], v[10:11], v[24:25]
	v_add_f32_e32 v12, v41, v12
	v_pk_add_f32 v[26:27], v[26:27], v[26:27] op_sel_hi:[0,1]
	v_add_f32_e32 v11, v40, v28
	v_exp_f32_e32 v25, v12
	v_add_f32_e32 v12, v40, v29
	v_exp_f32_e32 v11, v11
	v_exp_f32_e32 v26, v12
	v_add_f32_e32 v12, v41, v13
	v_exp_f32_e32 v12, v12
	v_lshlrev_b32_e32 v13, 3, v33
	v_and_b32_e32 v33, 8, v13
	v_add_f32_e32 v13, v25, v11
	v_pk_add_f32 v[28:29], v[12:13], v[26:27]
	v_add_f32_e32 v14, v41, v14
	v_pk_add_f32 v[28:29], v[28:29], v[28:29] op_sel_hi:[0,1]
	v_add_f32_e32 v13, v40, v30
	v_exp_f32_e32 v27, v14
	v_add_f32_e32 v14, v40, v31
	v_exp_f32_e32 v13, v13
	v_exp_f32_e32 v28, v14
	v_add_f32_e32 v14, v41, v15
	v_exp_f32_e32 v14, v14
	v_add_f32_e32 v15, v27, v13
	v_or3_b32 v235, v37, v35, v33
	s_mov_b32 s72, 0
	v_pk_add_f32 v[30:31], v[14:15], v[28:29]
	v_cvt_pk_bf16_f32 v152, v42, v0
	v_cvt_pk_bf16_f32 v153, v1, v38
	v_cvt_pk_bf16_f32 v154, v3, v18
	v_cvt_pk_bf16_f32 v155, v5, v20
	v_cvt_pk_bf16_f32 v156, v7, v22
	s_nop 0
	v_add_f32_e32 v15, v30, v31
	v_add_f32_e32 v229, 0, v15
	v_cvt_pk_bf16_f32 v157, v9, v24
	v_cvt_pk_bf16_f32 v158, v11, v26
	v_cvt_pk_bf16_f32 v159, v13, v28
	v_cvt_pk_bf16_f32 v148, v43, v16
	v_cvt_pk_bf16_f32 v149, v17, v2
	v_cvt_pk_bf16_f32 v150, v39, v4
	v_cvt_pk_bf16_f32 v151, v19, v6
	v_cvt_pk_bf16_f32 v160, v21, v8
	v_cvt_pk_bf16_f32 v161, v23, v10
	v_cvt_pk_bf16_f32 v162, v25, v12
	v_cvt_pk_bf16_f32 v163, v27, v14
	s_cmp_lt_i32 s82, 2
	v_xor_b32_e32 v236, 0x80, v235
	v_xor_b32_e32 v234, 0xc0, v235
	s_cbranch_scc1 .LBB0_331
	s_mov_b32 s97, s83
	s_lshl_b64 s[0:1], s[96:97], 13
	v_lshl_add_u64 v[0:1], v[212:213], 0, s[0:1]
	s_mov_b64 s[0:1], 0x106000
	v_lshl_add_u64 v[218:219], v[0:1], 0, s[0:1]
	s_mov_b64 s[0:1], 0x6000
	v_lshl_add_u64 v[220:221], v[0:1], 0, s[0:1]
	s_lshl_b64 s[0:1], s[96:97], 14
	v_lshl_add_u64 v[0:1], v[214:215], 0, s[0:1]
	s_mov_b64 s[4:5], 0xc000
	v_lshl_add_u64 v[222:223], v[0:1], 0, s[4:5]
	v_lshl_add_u64 v[0:1], v[216:217], 0, s[0:1]
	v_readlane_b32 s1, v244, 25
	s_add_i32 s1, s1, s2
	v_lshl_add_u64 v[224:225], v[0:1], 0, s[4:5]
	v_add_u32_e32 v0, s1, v32
	s_lshl_b32 s0, s96, 6
	v_sub_u32_e32 v0, v0, v34
	s_add_i32 s97, s0, 0x7f
	v_subrev_u32_e32 v240, s0, v0
	s_and_b32 s0, s74, 63
	s_lshl_b32 s0, s0, 7
	v_mov_b32_e32 v0, 0
	v_mul_f32_e32 v237, 0x42000000, v208
	v_add_u32_e32 v238, 0, v36
	v_xor_b32_e32 v239, 64, v235
	s_add_i32 s73, s33, -2
	s_add_i32 s79, s77, 0x18000
	s_sub_i32 s74, 0, s0
	v_mov_b32_e32 v1, v0
	v_mov_b32_e32 v2, v0
	v_mov_b32_e32 v3, v0
	v_mov_b32_e32 v4, v0
	v_mov_b32_e32 v5, v0
	v_mov_b32_e32 v6, v0
	v_mov_b32_e32 v7, v0
	v_mov_b32_e32 v8, v0
	v_mov_b32_e32 v9, v0
	v_mov_b32_e32 v10, v0
	v_mov_b32_e32 v11, v0
	v_mov_b32_e32 v12, v0
	v_mov_b32_e32 v13, v0
	v_mov_b32_e32 v14, v0
	v_mov_b32_e32 v15, v0
	v_mov_b32_e32 v16, v0
	v_mov_b32_e32 v17, v0
	v_mov_b32_e32 v18, v0
	v_mov_b32_e32 v19, v0
	v_mov_b32_e32 v20, v0
	v_mov_b32_e32 v21, v0
	v_mov_b32_e32 v22, v0
	v_mov_b32_e32 v23, v0
	v_mov_b32_e32 v24, v0
	v_mov_b32_e32 v25, v0
	v_mov_b32_e32 v26, v0
	v_mov_b32_e32 v27, v0
	v_mov_b32_e32 v28, v0
	v_mov_b32_e32 v29, v0
	v_mov_b32_e32 v30, v0
	v_mov_b32_e32 v31, v0
	v_mov_b32_e32 v32, v0
	v_mov_b32_e32 v33, v0
	v_mov_b32_e32 v34, v0
	v_mov_b32_e32 v35, v0
	v_mov_b32_e32 v36, v0
	v_mov_b32_e32 v37, v0
	v_mov_b32_e32 v38, v0
	v_mov_b32_e32 v39, v0
	v_mov_b32_e32 v40, v0
	v_mov_b32_e32 v41, v0
	v_mov_b32_e32 v42, v0
	v_mov_b32_e32 v43, v0
	v_mov_b32_e32 v44, v0
	v_mov_b32_e32 v45, v0
	v_mov_b32_e32 v46, v0
	v_mov_b32_e32 v47, v0
	v_mov_b32_e32 v48, v0
	v_mov_b32_e32 v49, v0
	v_mov_b32_e32 v50, v0
	v_mov_b32_e32 v51, v0
	v_mov_b32_e32 v52, v0
	v_mov_b32_e32 v53, v0
	v_mov_b32_e32 v54, v0
	v_mov_b32_e32 v55, v0
	v_mov_b32_e32 v56, v0
	v_mov_b32_e32 v57, v0
	v_mov_b32_e32 v58, v0
	v_mov_b32_e32 v59, v0
	v_mov_b32_e32 v60, v0
	v_mov_b32_e32 v61, v0
	v_mov_b32_e32 v62, v0
	v_mov_b32_e32 v63, v0
	v_mov_b32_e32 v166, v160
	v_mov_b32_e32 v167, v161
	v_mov_b32_e32 v168, v162
	v_mov_b32_e32 v169, v163
	v_mov_b32_e32 v162, v156
	v_mov_b32_e32 v163, v157
	v_mov_b32_e32 v164, v158
	v_mov_b32_e32 v165, v159
	v_mov_b32_e32 v174, v152
	v_mov_b32_e32 v175, v153
	v_mov_b32_e32 v176, v154
	v_mov_b32_e32 v177, v155
	v_mov_b32_e32 v170, v148
	v_mov_b32_e32 v171, v149
	v_mov_b32_e32 v172, v150
	v_mov_b32_e32 v173, v151
	s_cmp_ge_i32 s72, s73
	s_mov_b64 s[0:1], -1
	s_cbranch_scc0 .LBB0_321

.LBB0_323:
	s_and_b32 s1, s79, 0x18000
	s_xor_b32 s0, s1, 0x10000
	v_add_u32_e32 v84, s0, v238
	v_add_u32_e32 v85, v84, v230
	v_add_u32_e32 v254, v84, v231
	v_add_u32_e32 v255, v84, v232
	v_add_u32_e32 v84, v84, v233
	ds_read_b128 v[80:83], v85 offset:16384
	ds_read_b128 v[202:205], v254 offset:16384
	ds_read_b128 v[194:197], v255 offset:16384
	ds_read_b128 v[186:189], v84 offset:16384
	ds_read_b128 v[198:201], v85 offset:20480
	ds_read_b128 v[190:193], v254 offset:20480
	ds_read_b128 v[246:249], v255 offset:20480
	ds_read_b128 v[250:253], v84 offset:20480
	s_add_i32 s0, s72, 3
	s_cmp_ge_i32 s0, s33
	s_cbranch_scc1 .LBB0_325
	s_and_b32 s0, s79, 0x18000
	s_add_i32 m0, s0, s94
	s_add_i32 s1, s90, s0
	global_load_lds_dwordx4 v[220:221], off
	s_mov_b32 m0, s1
	s_add_i32 s1, s0, s66
	global_load_lds_dwordx4 v[218:219], off
	s_mov_b32 m0, s1
	v_lshl_add_u64 v[218:219], v[218:219], 0, s[88:89]
	global_load_lds_dwordx4 v[224:225], off
	global_load_lds_dwordx4 v[224:225], off offset:1024
	v_lshl_add_u64 v[220:221], v[220:221], 0, s[88:89]
	v_lshl_add_u64 v[224:225], v[224:225], 0, s[92:93]
.LBB0_325:
	s_waitcnt lgkmcnt(0)
	v_mfma_f32_32x32x16_bf16 v[96:111], v[80:83], v[144:147], v[64:79]
	s_add_i32 s0, s74, s97
	s_sub_i32 s0, s0, 63
	v_mfma_f32_32x32x16_bf16 v[96:111], v[202:205], v[140:143], v[96:111]
	v_cvt_f32_i32_e32 v156, s0
	v_mfma_f32_32x32x16_bf16 v[96:111], v[194:197], v[136:139], v[96:111]
	v_fma_f32 v254, v208, v156, -v207
	v_mfma_f32_32x32x16_bf16 v[96:111], v[186:189], v[132:135], v[96:111]
	v_add_f32_e32 v255, v237, v254
	s_add_i32 s3, s79, 0xfffe8000
	s_and_b32 s3, s3, 0x18000
	v_add_u32_e32 v158, s3, v235
	v_add_u32_e32 v159, s3, v239
	v_add_u32_e32 v160, s3, v236
	v_add_u32_e32 v161, s3, v234
	ds_read_b64_tr_b16 v[182:183], v158 offset:32768
	ds_read_b64_tr_b16 v[184:185], v158 offset:34816
	ds_read_b64_tr_b16 v[178:179], v159 offset:32768
	ds_read_b64_tr_b16 v[180:181], v159 offset:34816
	v_mfma_f32_32x32x16_bf16 v[80:95], v[198:201], v[144:147], v[64:79]
	v_add_f32_e32 v96, v254, v96
	v_exp_f32_e32 v96, v96
	v_add_f32_e32 v97, v254, v97
	v_exp_f32_e32 v97, v97
	v_add_f32_e32 v98, v254, v98
	v_exp_f32_e32 v98, v98
	v_add_f32_e32 v99, v254, v99
	v_exp_f32_e32 v99, v99
	v_mfma_f32_32x32x16_bf16 v[80:95], v[190:193], v[140:143], v[80:95]
	v_add_f32_e32 v100, v254, v100
	v_exp_f32_e32 v100, v100
	v_add_f32_e32 v101, v254, v101
	v_exp_f32_e32 v101, v101
	v_add_f32_e32 v102, v254, v102
	v_exp_f32_e32 v102, v102
	v_add_f32_e32 v103, v254, v103
	v_exp_f32_e32 v103, v103
	v_mfma_f32_32x32x16_bf16 v[80:95], v[246:249], v[136:139], v[80:95]
	v_add_f32_e32 v104, v254, v104
	v_exp_f32_e32 v104, v104
	v_add_f32_e32 v105, v254, v105
	v_exp_f32_e32 v105, v105
	v_add_f32_e32 v106, v254, v106
	v_exp_f32_e32 v106, v106
	v_add_f32_e32 v107, v254, v107
	v_exp_f32_e32 v107, v107
	v_mfma_f32_32x32x16_bf16 v[80:95], v[250:253], v[132:135], v[80:95]
	v_add_f32_e32 v108, v254, v108
	v_exp_f32_e32 v108, v108
	v_add_f32_e32 v109, v254, v109
	v_exp_f32_e32 v109, v109
	v_add_f32_e32 v110, v254, v110
	v_exp_f32_e32 v110, v110
	v_add_f32_e32 v111, v254, v111
	v_exp_f32_e32 v111, v111
	s_cmp_le_i32 s97, s78
	s_cbranch_scc1 .LBB0_327
	v_cmp_gt_i32_e64 s[60:61], 26, v240
	v_cmp_gt_i32_e64 s[62:63], 27, v240
	v_cmp_gt_i32_e64 s[58:59], 25, v240
	s_and_b64 s[60:61], s[62:63], s[60:61]
	v_cmp_gt_i32_e64 s[56:57], 24, v240
	s_and_b64 s[58:59], s[60:61], s[58:59]
	v_cmp_gt_i32_e64 s[54:55], 19, v240
	s_and_b64 s[56:57], s[58:59], s[56:57]
	v_cmp_gt_i32_e64 s[52:53], 18, v240
	s_and_b64 s[54:55], s[56:57], s[54:55]
	v_cmp_gt_i32_e64 s[50:51], 17, v240
	s_and_b64 s[52:53], s[54:55], s[52:53]
	v_cmp_gt_i32_e64 s[48:49], 16, v240
	s_and_b64 s[50:51], s[52:53], s[50:51]
	v_cmp_gt_i32_e64 s[46:47], 11, v240
	s_and_b64 s[48:49], s[50:51], s[48:49]
	v_cmp_gt_i32_e64 s[44:45], 10, v240
	s_and_b64 s[46:47], s[48:49], s[46:47]
	v_cmp_gt_i32_e64 s[42:43], 9, v240
	s_and_b64 s[44:45], s[46:47], s[44:45]
	v_cmp_gt_i32_e64 s[40:41], 8, v240
	s_and_b64 s[42:43], s[44:45], s[42:43]
	v_cmp_gt_i32_e64 s[38:39], 3, v240
	s_and_b64 s[40:41], s[42:43], s[40:41]
	v_cmp_gt_i32_e64 s[36:37], 2, v240
	s_and_b64 s[38:39], s[40:41], s[38:39]
	v_cmp_gt_i32_e64 s[34:35], 1, v240
	s_and_b64 s[36:37], s[38:39], s[36:37]
	v_cmp_gt_i32_e64 s[30:31], 0, v240
	s_and_b64 s[34:35], s[36:37], s[34:35]
	s_and_b64 s[30:31], s[34:35], s[30:31]
	v_cmp_gt_i32_e64 s[28:29], 58, v240
	v_cndmask_b32_e64 v96, v96, v113, s[30:31]
	v_cmp_gt_i32_e64 s[30:31], 59, v240
	v_cmp_gt_i32_e64 s[26:27], 57, v240
	s_and_b64 s[28:29], s[30:31], s[28:29]
	v_cmp_gt_i32_e64 s[24:25], 56, v240
	s_and_b64 s[26:27], s[28:29], s[26:27]
	v_cmp_gt_i32_e64 s[22:23], 51, v240
	s_and_b64 s[24:25], s[26:27], s[24:25]
	v_cmp_gt_i32_e64 s[20:21], 50, v240
	s_and_b64 s[22:23], s[24:25], s[22:23]
	v_cmp_gt_i32_e64 s[18:19], 49, v240
	s_and_b64 s[20:21], s[22:23], s[20:21]
	v_cmp_gt_i32_e64 s[16:17], 48, v240
	s_and_b64 s[18:19], s[20:21], s[18:19]
	v_cmp_gt_i32_e64 s[14:15], 43, v240
	s_and_b64 s[16:17], s[18:19], s[16:17]
	v_cmp_gt_i32_e64 s[12:13], 42, v240
	s_and_b64 s[14:15], s[16:17], s[14:15]
	v_cmp_gt_i32_e64 s[10:11], 41, v240
	s_and_b64 s[12:13], s[14:15], s[12:13]
	v_cmp_gt_i32_e64 s[8:9], 40, v240
	s_and_b64 s[10:11], s[12:13], s[10:11]
	v_cmp_gt_i32_e64 s[6:7], 35, v240
	s_and_b64 s[8:9], s[10:11], s[8:9]
	v_cmp_gt_i32_e64 s[4:5], 34, v240
	s_and_b64 s[6:7], s[8:9], s[6:7]
	v_cmp_gt_i32_e64 s[0:1], 33, v240
	s_and_b64 s[4:5], s[6:7], s[4:5]
	v_cmp_gt_i32_e32 vcc, 32, v240
	s_and_b64 s[0:1], s[4:5], s[0:1]
	s_and_b64 vcc, s[0:1], vcc
	v_cndmask_b32_e64 v111, v111, v113, s[62:63]
	v_cndmask_b32_e64 v110, v110, v113, s[60:61]
	v_cndmask_b32_e64 v109, v109, v113, s[58:59]
	v_cndmask_b32_e64 v108, v108, v113, s[56:57]
	v_cndmask_b32_e64 v107, v107, v113, s[54:55]
	v_cndmask_b32_e64 v106, v106, v113, s[52:53]
	v_cndmask_b32_e64 v105, v105, v113, s[50:51]
	v_cndmask_b32_e64 v104, v104, v113, s[48:49]
	v_cndmask_b32_e64 v103, v103, v113, s[46:47]
	v_cndmask_b32_e64 v102, v102, v113, s[44:45]
	v_cndmask_b32_e64 v101, v101, v113, s[42:43]
	v_cndmask_b32_e64 v100, v100, v113, s[40:41]
	v_cndmask_b32_e64 v99, v99, v113, s[38:39]
	v_cndmask_b32_e64 v98, v98, v113, s[36:37]
	v_cndmask_b32_e64 v97, v97, v113, s[34:35]
	v_cndmask_b32_e64 v95, v95, v228, s[30:31]
	v_cndmask_b32_e64 v94, v94, v228, s[28:29]
	v_cndmask_b32_e64 v93, v93, v228, s[26:27]
	v_cndmask_b32_e64 v92, v92, v228, s[24:25]
	v_cndmask_b32_e64 v91, v91, v228, s[22:23]
	v_cndmask_b32_e64 v90, v90, v228, s[20:21]
	v_cndmask_b32_e64 v89, v89, v228, s[18:19]
	v_cndmask_b32_e64 v88, v88, v228, s[16:17]
	v_cndmask_b32_e64 v87, v87, v228, s[14:15]
	v_cndmask_b32_e64 v86, v86, v228, s[12:13]
	v_cndmask_b32_e64 v85, v85, v228, s[10:11]
	v_cndmask_b32_e64 v84, v84, v228, s[8:9]
	v_cndmask_b32_e64 v83, v83, v228, s[6:7]
	v_cndmask_b32_e64 v82, v82, v228, s[4:5]
	v_cndmask_b32_e64 v81, v81, v228, s[0:1]
	v_cndmask_b32_e32 v80, v80, v228, vcc
.LBB0_327:
	s_waitcnt lgkmcnt(2)
	v_mfma_f32_32x32x16_bf16 v[48:63], v[182:185], v[174:177], v[48:63]
	v_add_f32_e32 v190, v255, v80
	v_exp_f32_e32 v190, v190
	ds_read_b64_tr_b16 v[148:149], v160 offset:32768
	ds_read_b64_tr_b16 v[150:151], v160 offset:34816
	v_add_f32_e32 v157, v190, v96
	s_waitcnt lgkmcnt(2)
	v_mfma_f32_32x32x16_bf16 v[32:47], v[178:181], v[174:177], v[32:47]
	v_add_f32_e32 v191, v255, v81
	v_exp_f32_e32 v191, v191
	ds_read_b64_tr_b16 v[152:153], v161 offset:32768
	ds_read_b64_tr_b16 v[154:155], v161 offset:34816
	v_add_f32_e32 v156, v191, v97
	v_add_f32_e32 v157, v156, v157
	s_waitcnt lgkmcnt(2)
	v_mfma_f32_32x32x16_bf16 v[16:31], v[148:151], v[174:177], v[16:31]
	v_add_f32_e32 v192, v255, v82
	v_exp_f32_e32 v192, v192
	ds_read_b64_tr_b16 v[182:183], v158 offset:36864
	ds_read_b64_tr_b16 v[184:185], v158 offset:38912
	v_add_f32_e32 v156, v192, v98
	v_add_f32_e32 v157, v156, v157
	s_waitcnt lgkmcnt(2)
	v_mfma_f32_32x32x16_bf16 v[0:15], v[152:155], v[174:177], v[0:15]
	v_add_f32_e32 v193, v255, v83
	v_exp_f32_e32 v193, v193
	ds_read_b64_tr_b16 v[178:179], v159 offset:36864
	ds_read_b64_tr_b16 v[180:181], v159 offset:38912
	v_add_f32_e32 v156, v193, v99
	v_add_f32_e32 v157, v156, v157
	v_cvt_pk_bf16_f32 v174, v96, v97
	s_waitcnt lgkmcnt(2)
	v_mfma_f32_32x32x16_bf16 v[48:63], v[182:185], v[162:165], v[48:63]
	v_add_f32_e32 v194, v255, v84
	v_exp_f32_e32 v194, v194
	ds_read_b64_tr_b16 v[148:149], v160 offset:36864
	ds_read_b64_tr_b16 v[150:151], v160 offset:38912
	v_add_f32_e32 v156, v194, v100
	v_add_f32_e32 v157, v156, v157
	v_cvt_pk_bf16_f32 v175, v98, v99
	s_waitcnt lgkmcnt(2)
	v_mfma_f32_32x32x16_bf16 v[32:47], v[178:181], v[162:165], v[32:47]
	v_add_f32_e32 v195, v255, v85
	v_exp_f32_e32 v195, v195
	ds_read_b64_tr_b16 v[152:153], v161 offset:36864
	ds_read_b64_tr_b16 v[154:155], v161 offset:38912
	v_add_f32_e32 v156, v195, v101
	v_add_f32_e32 v157, v156, v157
	v_cvt_pk_bf16_f32 v176, v100, v101
	s_waitcnt lgkmcnt(2)
	v_mfma_f32_32x32x16_bf16 v[16:31], v[148:151], v[162:165], v[16:31]
	v_add_f32_e32 v196, v255, v86
	v_exp_f32_e32 v196, v196
	ds_read_b64_tr_b16 v[182:183], v158 offset:40960
	ds_read_b64_tr_b16 v[184:185], v158 offset:43008
	v_add_f32_e32 v156, v196, v102
	v_add_f32_e32 v157, v156, v157
	v_cvt_pk_bf16_f32 v177, v102, v103
	s_waitcnt lgkmcnt(2)
	v_mfma_f32_32x32x16_bf16 v[0:15], v[152:155], v[162:165], v[0:15]
	v_add_f32_e32 v197, v255, v87
	v_exp_f32_e32 v197, v197
	ds_read_b64_tr_b16 v[178:179], v159 offset:40960
	ds_read_b64_tr_b16 v[180:181], v159 offset:43008
	v_add_f32_e32 v156, v197, v103
	v_add_f32_e32 v157, v156, v157
	v_cvt_pk_bf16_f32 v162, v104, v105
	s_waitcnt lgkmcnt(2)
	v_mfma_f32_32x32x16_bf16 v[48:63], v[182:185], v[170:173], v[48:63]
	v_add_f32_e32 v198, v255, v88
	v_exp_f32_e32 v198, v198
	ds_read_b64_tr_b16 v[148:149], v160 offset:40960
	ds_read_b64_tr_b16 v[150:151], v160 offset:43008
	v_add_f32_e32 v156, v198, v104
	v_add_f32_e32 v157, v156, v157
	v_cvt_pk_bf16_f32 v163, v106, v107
	s_waitcnt lgkmcnt(2)
	v_mfma_f32_32x32x16_bf16 v[32:47], v[178:181], v[170:173], v[32:47]
	v_add_f32_e32 v199, v255, v89
	v_exp_f32_e32 v199, v199
	ds_read_b64_tr_b16 v[152:153], v161 offset:40960
	ds_read_b64_tr_b16 v[154:155], v161 offset:43008
	v_add_f32_e32 v156, v199, v105
	v_add_f32_e32 v157, v156, v157
	v_cvt_pk_bf16_f32 v164, v108, v109
	s_waitcnt lgkmcnt(2)
	v_mfma_f32_32x32x16_bf16 v[16:31], v[148:151], v[170:173], v[16:31]
	v_add_f32_e32 v200, v255, v90
	v_exp_f32_e32 v200, v200
	ds_read_b64_tr_b16 v[182:183], v158 offset:45056
	ds_read_b64_tr_b16 v[184:185], v158 offset:47104
	v_add_f32_e32 v156, v200, v106
	v_add_f32_e32 v157, v156, v157
	v_cvt_pk_bf16_f32 v165, v110, v111
	s_waitcnt lgkmcnt(2)
	v_mfma_f32_32x32x16_bf16 v[0:15], v[152:155], v[170:173], v[0:15]
	v_add_f32_e32 v201, v255, v91
	v_exp_f32_e32 v201, v201
	ds_read_b64_tr_b16 v[178:179], v159 offset:45056
	ds_read_b64_tr_b16 v[180:181], v159 offset:47104
	v_add_f32_e32 v156, v201, v107
	v_add_f32_e32 v157, v156, v157
	v_cvt_pk_bf16_f32 v170, v190, v191
	s_waitcnt lgkmcnt(2)
	v_mfma_f32_32x32x16_bf16 v[48:63], v[182:185], v[166:169], v[48:63]
	v_add_f32_e32 v202, v255, v92
	v_exp_f32_e32 v202, v202
	ds_read_b64_tr_b16 v[148:149], v160 offset:45056
	ds_read_b64_tr_b16 v[150:151], v160 offset:47104
	v_add_f32_e32 v156, v202, v108
	v_add_f32_e32 v157, v156, v157
	v_cvt_pk_bf16_f32 v171, v192, v193
	s_waitcnt lgkmcnt(2)
	v_mfma_f32_32x32x16_bf16 v[32:47], v[178:181], v[166:169], v[32:47]
	v_add_f32_e32 v203, v255, v93
	v_exp_f32_e32 v203, v203
	ds_read_b64_tr_b16 v[152:153], v161 offset:45056
	ds_read_b64_tr_b16 v[154:155], v161 offset:47104
	v_add_f32_e32 v156, v203, v109
	v_add_f32_e32 v157, v156, v157
	v_cvt_pk_bf16_f32 v172, v194, v195
	s_waitcnt lgkmcnt(2)
	v_mfma_f32_32x32x16_bf16 v[16:31], v[148:151], v[166:169], v[16:31]
	v_add_f32_e32 v204, v255, v94
	v_exp_f32_e32 v204, v204
	s_nop 0
	v_add_f32_e32 v156, v204, v110
	v_add_f32_e32 v157, v156, v157
	v_cvt_pk_bf16_f32 v173, v196, v197
	s_waitcnt lgkmcnt(0)
	v_mfma_f32_32x32x16_bf16 v[0:15], v[152:155], v[166:169], v[0:15]
	v_add_f32_e32 v205, v255, v95
	v_exp_f32_e32 v205, v205
	s_nop 0
	v_add_f32_e32 v156, v205, v111
	v_add_f32_e32 v157, v156, v157
	v_cvt_pk_bf16_f32 v166, v198, v199
	v_cvt_pk_bf16_f32 v167, v200, v201
	v_cvt_pk_bf16_f32 v168, v202, v203
	v_cvt_pk_bf16_f32 v169, v204, v205
	s_add_i32 s0, s72, 1
	s_add_i32 s79, s79, 0x8000
	s_add_i32 s97, s97, 64
	s_add_i32 s1, s72, 2
	v_add_f32_e32 v229, v229, v157
	s_cmp_ge_i32 s1, s82
	v_subrev_u32_e32 v240, 64, v240
	s_cbranch_scc1 .LBB0_332
	s_mov_b32 s72, s0
	s_cmp_ge_i32 s72, s73
	s_mov_b64 s[0:1], -1
	s_cbranch_scc1 .LBB0_320
	s_branch .LBB0_321

.LBB0_332:
	v_mov_b32_e32 v152, v174
	v_mov_b32_e32 v153, v175
	v_mov_b32_e32 v154, v176
	v_mov_b32_e32 v155, v177
	v_mov_b32_e32 v156, v162
	v_mov_b32_e32 v157, v163
	v_mov_b32_e32 v158, v164
	v_mov_b32_e32 v159, v165
	v_mov_b32_e32 v148, v170
	v_mov_b32_e32 v149, v171
	v_mov_b32_e32 v150, v172
	v_mov_b32_e32 v151, v173
	v_mov_b32_e32 v160, v166
	v_mov_b32_e32 v161, v167
	v_mov_b32_e32 v162, v168
	v_mov_b32_e32 v163, v169
	v_readlane_b32 s79, v244, 28
